# latent attention unit finalize: the eight sub-LN weight loads and the two lambda loads issued together behind one wait instead of ten serial round trips
# baseline (speedup 1.0000x reference)
.LBB0_910:
	v_add_f32_e32 v1, 0, v101
	v_add_f32_e32 v1, v102, v1
	v_add_f32_e32 v1, v103, v1
	v_add_f32_e32 v1, v104, v1
	v_add_f32_e32 v1, v105, v1
	v_add_f32_e32 v1, v106, v1
	v_add_f32_e32 v1, v107, v1
	v_add_f32_e32 v1, v108, v1
	v_add_f32_e32 v1, v109, v1
	v_add_f32_e32 v1, v110, v1
	v_add_f32_e32 v1, v111, v1
	v_add_f32_e32 v1, v112, v1
	v_add_f32_e32 v1, v113, v1
	v_exp_f32_e32 v14, v80
	v_add_f32_e32 v1, v114, v1
	v_exp_f32_e32 v80, v81
	v_add_f32_e32 v1, v115, v1
	v_exp_f32_e32 v81, v82
	v_add_f32_e32 v1, v116, v1
	v_exp_f32_e32 v82, v83
	v_add_f32_e32 v1, v15, v1
	v_add_f32_e32 v15, 0, v14
	v_exp_f32_e32 v83, v84
	v_exp_f32_e32 v84, v85
	v_exp_f32_e32 v85, v86
	v_exp_f32_e32 v86, v87
	v_add_f32_e32 v15, v80, v15
	v_add_f32_e32 v15, v81, v15
	v_add_f32_e32 v15, v82, v15
	v_readlane_b32 s4, v255, 43
	v_add_f32_e32 v15, v83, v15
	v_cvt_pkrtz_f16_f32 v80, v14, v80
	v_cvt_pkrtz_f16_f32 v81, v81, v82
	v_cvt_pkrtz_f16_f32 v82, v83, v84
	v_cvt_pkrtz_f16_f32 v83, v85, v86
	v_readlane_b32 s5, v255, 44
	s_waitcnt vmcnt(0)
	s_nop 0
	v_mfma_f32_32x32x16_f16 v[64:79], v[2:5], v[80:83], v[64:79]
	v_mov_b64_e32 v[2:3], s[4:5]
	s_barrier
	flat_load_dword v4, v[2:3] sc0 sc1
	v_readlane_b32 s4, v255, 45
	v_readlane_b32 s5, v255, 46
	v_exp_f32_e32 v87, v88
	v_add_f32_e32 v15, v84, v15
	v_mov_b64_e32 v[102:103], s[4:5]
	v_exp_f32_e32 v88, v89
	v_mfma_f32_32x32x16_f16 v[48:63], v[6:9], v[80:83], v[48:63]
	flat_load_dword v6, v[102:103] sc0 sc1
	global_load_dwordx4 v[104:107], v210, s[34:35]
	global_load_dwordx4 v[108:111], v210, s[34:35] offset:32
	global_load_dwordx4 v[112:115], v210, s[34:35] offset:64
	global_load_dwordx4 v[116:119], v210, s[34:35] offset:96
	global_load_dwordx4 v[120:123], v210, s[34:35] offset:128
	global_load_dwordx4 v[124:127], v210, s[34:35] offset:160
	global_load_dwordx4 v[128:131], v210, s[34:35] offset:192
	global_load_dwordx4 v[132:135], v210, s[34:35] offset:224
	s_waitcnt vmcnt(0)
	ds_bpermute_b32 v2, v153, v1
	v_add_f32_e32 v15, v85, v15
	v_exp_f32_e32 v89, v90
	v_add_f32_e32 v15, v86, v15
	v_exp_f32_e32 v90, v91
	v_add_f32_e32 v15, v87, v15
	v_exp_f32_e32 v91, v92
	v_add_f32_e32 v15, v88, v15
	v_exp_f32_e32 v92, v93
	v_add_f32_e32 v15, v89, v15
	v_exp_f32_e32 v93, v94
	s_waitcnt lgkmcnt(0)
	v_add_f32_e32 v1, v1, v2
	v_add_f32_e32 v15, v90, v15
	v_exp_f32_e32 v94, v95
	v_div_scale_f32 v3, s[4:5], v1, v1, 1.0
	v_add_f32_e32 v15, v91, v15
	v_rcp_f32_e32 v5, v3
	v_add_f32_e32 v15, v92, v15
	v_add_f32_e32 v15, v93, v15
	v_add_f32_e32 v15, v94, v15
	v_add_f32_e32 v15, v100, v15
	v_fma_f32 v7, -v3, v5, 1.0
	ds_bpermute_b32 v2, v153, v15
	v_fmac_f32_e32 v5, v7, v5
	v_div_scale_f32 v7, vcc, 1.0, v1, 1.0
	v_mul_f32_e32 v8, v7, v5
	v_fma_f32 v9, -v3, v8, v7
	v_fmac_f32_e32 v8, v9, v5
	v_fma_f32 v3, -v3, v8, v7
	v_cvt_pkrtz_f16_f32 v84, v87, v88
	v_cvt_pkrtz_f16_f32 v85, v89, v90
	v_cvt_pkrtz_f16_f32 v86, v91, v92
	v_cvt_pkrtz_f16_f32 v87, v93, v94
	s_waitcnt lgkmcnt(0)
	v_add_f32_e32 v2, v15, v2
	v_div_fmas_f32 v3, v3, v5, v8
	v_mfma_f32_32x32x16_f16 v[64:79], v[10:13], v[84:87], v[64:79]
	v_div_fixup_f32 v12, v3, v1, 1.0
	s_mov_b32 s3, s59
	v_div_scale_f32 v1, s[4:5], v2, v2, v4
	v_rcp_f32_e32 v3, v1
	v_mfma_f32_32x32x16_f16 v[48:63], v[96:99], v[84:87], v[48:63]
	v_fma_f32 v5, -v1, v3, 1.0
	v_fmac_f32_e32 v3, v5, v3
	v_div_scale_f32 v5, vcc, v4, v2, v4
	v_mul_f32_e32 v7, v5, v3
	v_fma_f32 v8, -v1, v7, v5
	v_fmac_f32_e32 v7, v8, v3
	v_fma_f32 v1, -v1, v7, v5
	v_div_fmas_f32 v1, v1, v3, v7
	v_div_fixup_f32 v14, v1, v2, v4
	s_nop 1
	s_nop 0
	v_pk_mul_f32 v[48:49], v[48:49], v[14:15] op_sel_hi:[1,0]
	v_pk_mul_f32 v[2:3], v[76:77], v[14:15] op_sel_hi:[1,0]
	v_pk_fma_f32 v[16:17], v[16:17], v[12:13], v[48:49] op_sel_hi:[1,0,1] neg_lo:[0,0,1] neg_hi:[0,0,1]
	v_pk_mul_f32 v[50:51], v[50:51], v[14:15] op_sel_hi:[1,0]
	v_pk_fma_f32 v[4:5], v[44:45], v[12:13], v[2:3] op_sel_hi:[1,0,1] neg_lo:[0,0,1] neg_hi:[0,0,1]
	v_pk_mul_f32 v[2:3], v[78:79], v[14:15] op_sel_hi:[1,0]
	v_pk_mul_f32 v[48:49], v[16:17], v[16:17]
	v_pk_fma_f32 v[18:19], v[18:19], v[12:13], v[50:51] op_sel_hi:[1,0,1] neg_lo:[0,0,1] neg_hi:[0,0,1]
	v_pk_mul_f32 v[52:53], v[52:53], v[14:15] op_sel_hi:[1,0]
	v_pk_mul_f32 v[54:55], v[54:55], v[14:15] op_sel_hi:[1,0]
	v_pk_mul_f32 v[56:57], v[56:57], v[14:15] op_sel_hi:[1,0]
	v_pk_mul_f32 v[58:59], v[58:59], v[14:15] op_sel_hi:[1,0]
	v_pk_mul_f32 v[60:61], v[60:61], v[14:15] op_sel_hi:[1,0]
	v_pk_mul_f32 v[62:63], v[62:63], v[14:15] op_sel_hi:[1,0]
	v_pk_mul_f32 v[64:65], v[64:65], v[14:15] op_sel_hi:[1,0]
	v_pk_mul_f32 v[66:67], v[66:67], v[14:15] op_sel_hi:[1,0]
	v_pk_mul_f32 v[68:69], v[68:69], v[14:15] op_sel_hi:[1,0]
	v_pk_mul_f32 v[70:71], v[70:71], v[14:15] op_sel_hi:[1,0]
	v_pk_mul_f32 v[72:73], v[72:73], v[14:15] op_sel_hi:[1,0]
	v_pk_mul_f32 v[14:15], v[74:75], v[14:15] op_sel_hi:[1,0]
	v_pk_fma_f32 v[2:3], v[46:47], v[12:13], v[2:3] op_sel_hi:[1,0,1] neg_lo:[0,0,1] neg_hi:[0,0,1]
	v_pk_mul_f32 v[50:51], v[18:19], v[18:19]
	v_pk_fma_f32 v[20:21], v[20:21], v[12:13], v[52:53] op_sel_hi:[1,0,1] neg_lo:[0,0,1] neg_hi:[0,0,1]
	v_pk_fma_f32 v[22:23], v[22:23], v[12:13], v[54:55] op_sel_hi:[1,0,1] neg_lo:[0,0,1] neg_hi:[0,0,1]
	v_pk_fma_f32 v[24:25], v[24:25], v[12:13], v[56:57] op_sel_hi:[1,0,1] neg_lo:[0,0,1] neg_hi:[0,0,1]
	v_pk_fma_f32 v[26:27], v[26:27], v[12:13], v[58:59] op_sel_hi:[1,0,1] neg_lo:[0,0,1] neg_hi:[0,0,1]
	v_pk_fma_f32 v[28:29], v[28:29], v[12:13], v[60:61] op_sel_hi:[1,0,1] neg_lo:[0,0,1] neg_hi:[0,0,1]
	v_pk_fma_f32 v[30:31], v[30:31], v[12:13], v[62:63] op_sel_hi:[1,0,1] neg_lo:[0,0,1] neg_hi:[0,0,1]
	v_pk_fma_f32 v[32:33], v[32:33], v[12:13], v[64:65] op_sel_hi:[1,0,1] neg_lo:[0,0,1] neg_hi:[0,0,1]
	v_pk_fma_f32 v[34:35], v[34:35], v[12:13], v[66:67] op_sel_hi:[1,0,1] neg_lo:[0,0,1] neg_hi:[0,0,1]
	v_pk_fma_f32 v[36:37], v[36:37], v[12:13], v[68:69] op_sel_hi:[1,0,1] neg_lo:[0,0,1] neg_hi:[0,0,1]
	v_pk_fma_f32 v[38:39], v[38:39], v[12:13], v[70:71] op_sel_hi:[1,0,1] neg_lo:[0,0,1] neg_hi:[0,0,1]
	v_pk_fma_f32 v[40:41], v[40:41], v[12:13], v[72:73] op_sel_hi:[1,0,1] neg_lo:[0,0,1] neg_hi:[0,0,1]
	v_pk_fma_f32 v[12:13], v[42:43], v[12:13], v[14:15] op_sel_hi:[1,0,1] neg_lo:[0,0,1] neg_hi:[0,0,1]
	v_add_f32_e32 v42, v48, v49
	v_add_f32_e32 v42, v50, v42
	v_pk_mul_f32 v[52:53], v[20:21], v[20:21]
	v_add_f32_e32 v42, v51, v42
	v_add_f32_e32 v42, v52, v42
	v_pk_mul_f32 v[54:55], v[22:23], v[22:23]
	v_add_f32_e32 v42, v53, v42
	v_add_f32_e32 v42, v54, v42
	v_pk_mul_f32 v[56:57], v[24:25], v[24:25]
	v_add_f32_e32 v42, v55, v42
	v_add_f32_e32 v42, v56, v42
	v_pk_mul_f32 v[58:59], v[26:27], v[26:27]
	v_add_f32_e32 v42, v57, v42
	v_add_f32_e32 v42, v58, v42
	v_pk_mul_f32 v[60:61], v[28:29], v[28:29]
	v_add_f32_e32 v42, v59, v42
	v_add_f32_e32 v42, v60, v42
	v_pk_mul_f32 v[62:63], v[30:31], v[30:31]
	v_add_f32_e32 v42, v61, v42
	v_add_f32_e32 v42, v62, v42
	v_pk_mul_f32 v[64:65], v[32:33], v[32:33]
	v_add_f32_e32 v42, v63, v42
	v_add_f32_e32 v42, v64, v42
	v_pk_mul_f32 v[66:67], v[34:35], v[34:35]
	v_add_f32_e32 v42, v65, v42
	v_add_f32_e32 v42, v66, v42
	v_pk_mul_f32 v[68:69], v[36:37], v[36:37]
	v_add_f32_e32 v42, v67, v42
	v_add_f32_e32 v42, v68, v42
	v_pk_mul_f32 v[70:71], v[38:39], v[38:39]
	v_add_f32_e32 v42, v69, v42
	v_add_f32_e32 v42, v70, v42
	v_pk_mul_f32 v[72:73], v[40:41], v[40:41]
	v_add_f32_e32 v42, v71, v42
	v_add_f32_e32 v42, v72, v42
	v_pk_mul_f32 v[14:15], v[12:13], v[12:13]
	v_add_f32_e32 v42, v73, v42
	v_add_f32_e32 v14, v14, v42
	v_pk_mul_f32 v[44:45], v[4:5], v[4:5]
	v_add_f32_e32 v14, v15, v14
	v_add_f32_e32 v14, v44, v14
	v_pk_mul_f32 v[46:47], v[2:3], v[2:3]
	v_add_f32_e32 v14, v45, v14
	v_add_f32_e32 v14, v46, v14
	v_add_f32_e32 v14, v47, v14
	ds_bpermute_b32 v15, v153, v14
	v_sub_f32_e32 v1, 1.0, v6
	v_lshlrev_b64 v[6:7], 11, v[148:149]
	v_lshl_add_u64 v[6:7], s[64:65], 0, v[6:7]
	v_lshl_add_u64 v[6:7], v[6:7], 0, s[2:3]
	s_waitcnt lgkmcnt(0)
	v_add_f32_e32 v14, v14, v15
	v_fmamk_f32 v14, v14, 0x3c800000, v213
	v_cmp_gt_f32_e32 vcc, s38, v14
	v_mul_f32_e32 v15, 0x4b800000, v14
	v_lshlrev_b32_e32 v76, 3, v152
	v_cndmask_b32_e32 v14, v14, v15, vcc
	v_rsq_f32_e32 v14, v14
	v_mov_b32_e32 v77, v211
	v_lshl_add_u64 v[6:7], v[6:7], 0, v[76:77]
	v_mul_f32_e32 v15, 0x45800000, v14
	v_cndmask_b32_e32 v14, v14, v15, vcc
	v_mul_f32_e32 v14, v1, v14
	v_pk_mul_f32 v[16:17], v[16:17], v[14:15] op_sel_hi:[1,0]
	v_pk_mul_f32 v[12:13], v[12:13], v[14:15] op_sel_hi:[1,0]
	v_pk_mul_f32 v[8:9], v[104:105], v[16:17]
	v_pk_mul_f32 v[16:17], v[18:19], v[14:15] op_sel_hi:[1,0]
	v_cvt_pk_f16_f32 v8, v8, v9
	v_pk_mul_f32 v[10:11], v[106:107], v[16:17]
	v_pk_mul_f32 v[16:17], v[20:21], v[14:15] op_sel_hi:[1,0]
	v_cvt_pk_f16_f32 v9, v10, v11
	global_store_dwordx2 v[6:7], v[8:9], off offset:1536
	v_pk_mul_f32 v[4:5], v[4:5], v[14:15] op_sel_hi:[1,0]
	v_pk_mul_f32 v[2:3], v[2:3], v[14:15] op_sel_hi:[1,0]
	v_pk_mul_f32 v[8:9], v[108:109], v[16:17]
	v_pk_mul_f32 v[16:17], v[22:23], v[14:15] op_sel_hi:[1,0]
	v_cvt_pk_f16_f32 v8, v8, v9
	v_pk_mul_f32 v[10:11], v[110:111], v[16:17]
	v_pk_mul_f32 v[16:17], v[24:25], v[14:15] op_sel_hi:[1,0]
	v_cvt_pk_f16_f32 v9, v10, v11
	global_store_dwordx2 v[6:7], v[8:9], off offset:1552
	v_pk_mul_f32 v[8:9], v[112:113], v[16:17]
	v_pk_mul_f32 v[16:17], v[26:27], v[14:15] op_sel_hi:[1,0]
	v_cvt_pk_f16_f32 v8, v8, v9
	v_pk_mul_f32 v[10:11], v[114:115], v[16:17]
	v_pk_mul_f32 v[16:17], v[28:29], v[14:15] op_sel_hi:[1,0]
	v_cvt_pk_f16_f32 v9, v10, v11
	global_store_dwordx2 v[6:7], v[8:9], off offset:1568
	v_pk_mul_f32 v[8:9], v[116:117], v[16:17]
	v_pk_mul_f32 v[16:17], v[30:31], v[14:15] op_sel_hi:[1,0]
	v_cvt_pk_f16_f32 v8, v8, v9
	v_pk_mul_f32 v[10:11], v[118:119], v[16:17]
	v_pk_mul_f32 v[16:17], v[32:33], v[14:15] op_sel_hi:[1,0]
	v_cvt_pk_f16_f32 v9, v10, v11
	global_store_dwordx2 v[6:7], v[8:9], off offset:1584
	v_pk_mul_f32 v[8:9], v[120:121], v[16:17]
	v_pk_mul_f32 v[16:17], v[34:35], v[14:15] op_sel_hi:[1,0]
	v_cvt_pk_f16_f32 v8, v8, v9
	v_pk_mul_f32 v[10:11], v[122:123], v[16:17]
	v_pk_mul_f32 v[16:17], v[36:37], v[14:15] op_sel_hi:[1,0]
	v_cvt_pk_f16_f32 v9, v10, v11
	global_store_dwordx2 v[6:7], v[8:9], off offset:1600
	v_pk_mul_f32 v[8:9], v[124:125], v[16:17]
	v_pk_mul_f32 v[16:17], v[38:39], v[14:15] op_sel_hi:[1,0]
	v_cvt_pk_f16_f32 v8, v8, v9
	v_pk_mul_f32 v[10:11], v[126:127], v[16:17]
	v_pk_mul_f32 v[16:17], v[40:41], v[14:15] op_sel_hi:[1,0]
	v_cvt_pk_f16_f32 v9, v10, v11
	global_store_dwordx2 v[6:7], v[8:9], off offset:1616
	v_pk_mul_f32 v[8:9], v[128:129], v[16:17]
	v_pk_mul_f32 v[10:11], v[130:131], v[12:13]
	v_cvt_pk_f16_f32 v8, v8, v9
	v_cvt_pk_f16_f32 v9, v10, v11
	global_store_dwordx2 v[6:7], v[8:9], off offset:1632
	v_pk_mul_f32 v[4:5], v[132:133], v[4:5]
	v_pk_mul_f32 v[2:3], v[134:135], v[2:3]
	v_cvt_pk_f16_f32 v4, v4, v5
	v_cvt_pk_f16_f32 v5, v2, v3
	global_store_dwordx2 v[6:7], v[4:5], off offset:1648
